# P3/P10 residual epilogue: 16 base loads in flight with counted vmcnt instead of one serialized load-wait-store per group
# baseline (speedup 1.0000x reference)
.LBB0_327:
	s_ashr_i32 s26, s76, 3
	s_mul_hi_i32 s27, s26, 0x9000
	s_mul_i32 s26, s26, 0x9000
	s_add_u32 s26, s58, s26
	v_lshl_or_b32 v144, s77, 8, v154
	s_addc_u32 s27, s59, s27
	v_ashrrev_i32_e32 v145, 31, v144
	v_lshl_add_u32 v150, s76, 8, v152
	v_lshl_add_u64 v[146:147], v[144:145], 2, s[26:27]
	v_ashrrev_i32_e32 v151, 31, v150
	global_load_dwordx4 v[158:161], v[146:147], off
	global_load_dwordx4 v[162:165], v[146:147], off offset:16
	global_load_dwordx4 v[166:169], v[146:147], off offset:512
	global_load_dwordx4 v[170:173], v[146:147], off offset:528
	v_lshlrev_b64 v[148:149], 10, v[150:151]
	v_lshl_add_u64 v[148:149], v[148:149], 0, v[144:145]
	v_lshlrev_b64 v[148:149], 2, v[148:149]
	v_lshl_add_u64 v[176:177], s[8:9], 0, v[148:149]
	v_lshl_add_u64 v[180:181], s[62:63], 0, v[148:149]
	s_mov_b64 s[78:79], 0x10000
	s_mov_b64 s[80:81], 0x50000
	s_and_b64 vcc, exec, s[4:5]
	s_mov_b64 s[4:5], -1
	global_load_dwordx4 v[184:187], v[176:177], off
	global_load_dwordx4 v[188:191], v[176:177], off offset:16
	global_load_dwordx4 v[192:195], v[176:177], off offset:512
	global_load_dwordx4 v[196:199], v[176:177], off offset:528
	v_lshl_add_u64 v[176:177], v[176:177], 0, s[78:79]
	global_load_dwordx4 v[200:203], v[176:177], off
	global_load_dwordx4 v[204:207], v[176:177], off offset:16
	global_load_dwordx4 v[212:215], v[176:177], off offset:512
	global_load_dwordx4 v[216:219], v[176:177], off offset:528
	v_lshl_add_u64 v[176:177], v[176:177], 0, s[78:79]
	global_load_dwordx4 v[220:223], v[176:177], off
	global_load_dwordx4 v[224:227], v[176:177], off offset:16
	global_load_dwordx4 v[228:231], v[176:177], off offset:512
	global_load_dwordx4 v[232:235], v[176:177], off offset:528
	v_lshl_add_u64 v[176:177], v[176:177], 0, s[78:79]
	global_load_dwordx4 v[236:239], v[176:177], off
	global_load_dwordx4 v[240:243], v[176:177], off offset:16
	global_load_dwordx4 v[244:247], v[176:177], off offset:512
	global_load_dwordx4 v[248:251], v[176:177], off offset:528
	v_lshl_add_u64 v[176:177], v[176:177], 0, s[80:81]
	s_waitcnt vmcnt(16)
	v_pk_mul_f32 v[158:159], v[158:159], 0.5 op_sel_hi:[1,0]
	v_pk_mul_f32 v[160:161], v[160:161], 0.5 op_sel_hi:[1,0]
	v_pk_mul_f32 v[162:163], v[162:163], 0.5 op_sel_hi:[1,0]
	v_pk_mul_f32 v[164:165], v[164:165], 0.5 op_sel_hi:[1,0]
	v_pk_mul_f32 v[166:167], v[166:167], 0.5 op_sel_hi:[1,0]
	v_pk_mul_f32 v[168:169], v[168:169], 0.5 op_sel_hi:[1,0]
	v_pk_mul_f32 v[170:171], v[170:171], 0.5 op_sel_hi:[1,0]
	v_pk_mul_f32 v[172:173], v[172:173], 0.5 op_sel_hi:[1,0]
	s_waitcnt vmcnt(15)
	v_pk_fma_f32 v[126:127], v[126:127], v[160:161], v[186:187]
	v_pk_fma_f32 v[124:125], v[124:125], v[158:159], v[184:185]
	global_store_dwordx4 v[180:181], v[124:127], off
	global_load_dwordx4 v[184:187], v[176:177], off
	s_waitcnt vmcnt(16)
	v_pk_fma_f32 v[122:123], v[122:123], v[164:165], v[190:191]
	v_pk_fma_f32 v[120:121], v[120:121], v[162:163], v[188:189]
	global_store_dwordx4 v[180:181], v[120:123], off offset:16
	global_load_dwordx4 v[188:191], v[176:177], off offset:16
	s_waitcnt vmcnt(17)
	v_pk_fma_f32 v[118:119], v[118:119], v[168:169], v[194:195]
	v_pk_fma_f32 v[116:117], v[116:117], v[166:167], v[192:193]
	global_store_dwordx4 v[180:181], v[116:119], off offset:512
	global_load_dwordx4 v[192:195], v[176:177], off offset:512
	s_waitcnt vmcnt(18)
	v_pk_fma_f32 v[106:107], v[106:107], v[172:173], v[198:199]
	v_pk_fma_f32 v[104:105], v[104:105], v[170:171], v[196:197]
	global_store_dwordx4 v[180:181], v[104:107], off offset:528
	v_lshl_add_u64 v[180:181], v[180:181], 0, s[78:79]
	global_load_dwordx4 v[196:199], v[176:177], off offset:528
	v_lshl_add_u64 v[176:177], v[176:177], 0, s[78:79]
	s_waitcnt vmcnt(19)
	v_pk_fma_f32 v[114:115], v[114:115], v[160:161], v[202:203]
	v_pk_fma_f32 v[112:113], v[112:113], v[158:159], v[200:201]
	global_store_dwordx4 v[180:181], v[112:115], off
	global_load_dwordx4 v[200:203], v[176:177], off
	s_waitcnt vmcnt(20)
	v_pk_fma_f32 v[110:111], v[110:111], v[164:165], v[206:207]
	v_pk_fma_f32 v[108:109], v[108:109], v[162:163], v[204:205]
	global_store_dwordx4 v[180:181], v[108:111], off offset:16
	global_load_dwordx4 v[204:207], v[176:177], off offset:16
	s_waitcnt vmcnt(21)
	v_pk_fma_f32 v[102:103], v[102:103], v[168:169], v[214:215]
	v_pk_fma_f32 v[100:101], v[100:101], v[166:167], v[212:213]
	global_store_dwordx4 v[180:181], v[100:103], off offset:512
	global_load_dwordx4 v[212:215], v[176:177], off offset:512
	s_waitcnt vmcnt(22)
	v_pk_fma_f32 v[90:91], v[90:91], v[172:173], v[218:219]
	v_pk_fma_f32 v[88:89], v[88:89], v[170:171], v[216:217]
	global_store_dwordx4 v[180:181], v[88:91], off offset:528
	v_lshl_add_u64 v[180:181], v[180:181], 0, s[78:79]
	global_load_dwordx4 v[216:219], v[176:177], off offset:528
	v_lshl_add_u64 v[176:177], v[176:177], 0, s[78:79]
	s_waitcnt vmcnt(23)
	v_pk_fma_f32 v[98:99], v[98:99], v[160:161], v[222:223]
	v_pk_fma_f32 v[96:97], v[96:97], v[158:159], v[220:221]
	global_store_dwordx4 v[180:181], v[96:99], off
	global_load_dwordx4 v[220:223], v[176:177], off
	s_waitcnt vmcnt(24)
	v_pk_fma_f32 v[94:95], v[94:95], v[164:165], v[226:227]
	v_pk_fma_f32 v[92:93], v[92:93], v[162:163], v[224:225]
	global_store_dwordx4 v[180:181], v[92:95], off offset:16
	global_load_dwordx4 v[224:227], v[176:177], off offset:16
	s_waitcnt vmcnt(25)
	v_pk_fma_f32 v[86:87], v[86:87], v[168:169], v[230:231]
	v_pk_fma_f32 v[84:85], v[84:85], v[166:167], v[228:229]
	global_store_dwordx4 v[180:181], v[84:87], off offset:512
	global_load_dwordx4 v[228:231], v[176:177], off offset:512
	s_waitcnt vmcnt(26)
	v_pk_fma_f32 v[74:75], v[74:75], v[172:173], v[234:235]
	v_pk_fma_f32 v[72:73], v[72:73], v[170:171], v[232:233]
	global_store_dwordx4 v[180:181], v[72:75], off offset:528
	v_lshl_add_u64 v[180:181], v[180:181], 0, s[78:79]
	global_load_dwordx4 v[232:235], v[176:177], off offset:528
	v_lshl_add_u64 v[176:177], v[176:177], 0, s[78:79]
	s_waitcnt vmcnt(27)
	v_pk_fma_f32 v[82:83], v[82:83], v[160:161], v[238:239]
	v_pk_fma_f32 v[80:81], v[80:81], v[158:159], v[236:237]
	global_store_dwordx4 v[180:181], v[80:83], off
	global_load_dwordx4 v[236:239], v[176:177], off
	s_waitcnt vmcnt(28)
	v_pk_fma_f32 v[78:79], v[78:79], v[164:165], v[242:243]
	v_pk_fma_f32 v[76:77], v[76:77], v[162:163], v[240:241]
	global_store_dwordx4 v[180:181], v[76:79], off offset:16
	global_load_dwordx4 v[240:243], v[176:177], off offset:16
	s_waitcnt vmcnt(29)
	v_pk_fma_f32 v[70:71], v[70:71], v[168:169], v[246:247]
	v_pk_fma_f32 v[68:69], v[68:69], v[166:167], v[244:245]
	global_store_dwordx4 v[180:181], v[68:71], off offset:512
	global_load_dwordx4 v[244:247], v[176:177], off offset:512
	s_waitcnt vmcnt(30)
	v_pk_fma_f32 v[66:67], v[66:67], v[172:173], v[250:251]
	v_pk_fma_f32 v[64:65], v[64:65], v[170:171], v[248:249]
	global_store_dwordx4 v[180:181], v[64:67], off offset:528
	v_lshl_add_u64 v[180:181], v[180:181], 0, s[80:81]
	global_load_dwordx4 v[248:251], v[176:177], off offset:528
	s_waitcnt vmcnt(30)
	v_pk_fma_f32 v[62:63], v[62:63], v[160:161], v[186:187]
	v_pk_fma_f32 v[60:61], v[60:61], v[158:159], v[184:185]
	global_store_dwordx4 v[180:181], v[60:63], off
	s_waitcnt vmcnt(29)
	v_pk_fma_f32 v[58:59], v[58:59], v[164:165], v[190:191]
	v_pk_fma_f32 v[56:57], v[56:57], v[162:163], v[188:189]
	global_store_dwordx4 v[180:181], v[56:59], off offset:16
	s_waitcnt vmcnt(28)
	v_pk_fma_f32 v[54:55], v[54:55], v[168:169], v[194:195]
	v_pk_fma_f32 v[52:53], v[52:53], v[166:167], v[192:193]
	global_store_dwordx4 v[180:181], v[52:55], off offset:512
	s_waitcnt vmcnt(27)
	v_pk_fma_f32 v[42:43], v[42:43], v[172:173], v[198:199]
	v_pk_fma_f32 v[40:41], v[40:41], v[170:171], v[196:197]
	global_store_dwordx4 v[180:181], v[40:43], off offset:528
	v_lshl_add_u64 v[180:181], v[180:181], 0, s[78:79]
	s_waitcnt vmcnt(26)
	v_pk_fma_f32 v[50:51], v[50:51], v[160:161], v[202:203]
	v_pk_fma_f32 v[48:49], v[48:49], v[158:159], v[200:201]
	global_store_dwordx4 v[180:181], v[48:51], off
	s_waitcnt vmcnt(25)
	v_pk_fma_f32 v[46:47], v[46:47], v[164:165], v[206:207]
	v_pk_fma_f32 v[44:45], v[44:45], v[162:163], v[204:205]
	global_store_dwordx4 v[180:181], v[44:47], off offset:16
	s_waitcnt vmcnt(24)
	v_pk_fma_f32 v[38:39], v[38:39], v[168:169], v[214:215]
	v_pk_fma_f32 v[36:37], v[36:37], v[166:167], v[212:213]
	global_store_dwordx4 v[180:181], v[36:39], off offset:512
	s_waitcnt vmcnt(23)
	v_pk_fma_f32 v[26:27], v[26:27], v[172:173], v[218:219]
	v_pk_fma_f32 v[24:25], v[24:25], v[170:171], v[216:217]
	global_store_dwordx4 v[180:181], v[24:27], off offset:528
	v_lshl_add_u64 v[180:181], v[180:181], 0, s[78:79]
	s_waitcnt vmcnt(22)
	v_pk_fma_f32 v[34:35], v[34:35], v[160:161], v[222:223]
	v_pk_fma_f32 v[32:33], v[32:33], v[158:159], v[220:221]
	global_store_dwordx4 v[180:181], v[32:35], off
	s_waitcnt vmcnt(21)
	v_pk_fma_f32 v[30:31], v[30:31], v[164:165], v[226:227]
	v_pk_fma_f32 v[28:29], v[28:29], v[162:163], v[224:225]
	global_store_dwordx4 v[180:181], v[28:31], off offset:16
	s_waitcnt vmcnt(20)
	v_pk_fma_f32 v[22:23], v[22:23], v[168:169], v[230:231]
	v_pk_fma_f32 v[20:21], v[20:21], v[166:167], v[228:229]
	global_store_dwordx4 v[180:181], v[20:23], off offset:512
	s_waitcnt vmcnt(19)
	v_pk_fma_f32 v[10:11], v[10:11], v[172:173], v[234:235]
	v_pk_fma_f32 v[8:9], v[8:9], v[170:171], v[232:233]
	global_store_dwordx4 v[180:181], v[8:11], off offset:528
	v_lshl_add_u64 v[180:181], v[180:181], 0, s[78:79]
	s_waitcnt vmcnt(18)
	v_pk_fma_f32 v[18:19], v[18:19], v[160:161], v[238:239]
	v_pk_fma_f32 v[16:17], v[16:17], v[158:159], v[236:237]
	global_store_dwordx4 v[180:181], v[16:19], off
	s_waitcnt vmcnt(17)
	v_pk_fma_f32 v[14:15], v[14:15], v[164:165], v[242:243]
	v_pk_fma_f32 v[12:13], v[12:13], v[162:163], v[240:241]
	global_store_dwordx4 v[180:181], v[12:15], off offset:16
	s_waitcnt vmcnt(16)
	v_pk_fma_f32 v[6:7], v[6:7], v[168:169], v[246:247]
	v_pk_fma_f32 v[4:5], v[4:5], v[166:167], v[244:245]
	global_store_dwordx4 v[180:181], v[4:7], off offset:512
	s_waitcnt vmcnt(15)
	v_pk_fma_f32 v[2:3], v[2:3], v[172:173], v[250:251]
	v_pk_fma_f32 v[0:1], v[0:1], v[170:171], v[248:249]
	global_store_dwordx4 v[180:181], v[0:3], off offset:528
	s_cbranch_vccnz .LBB0_312
	s_andn2_b64 vcc, exec, s[0:1]
	s_cbranch_vccnz .LBB0_311
	s_barrier
	s_branch .LBB0_311

.LBB0_1127:
	s_ashr_i32 s18, s48, 3
	s_mul_hi_i32 s19, s18, 0x9000
	s_mul_i32 s18, s18, 0x9000
	s_add_u32 s18, s35, s18
	v_lshl_or_b32 v144, s49, 8, v154
	s_addc_u32 s19, s36, s19
	v_ashrrev_i32_e32 v145, 31, v144
	v_lshl_add_u32 v150, s48, 8, v152
	v_lshl_add_u64 v[146:147], v[144:145], 2, s[18:19]
	v_ashrrev_i32_e32 v151, 31, v150
	global_load_dwordx4 v[158:161], v[146:147], off
	global_load_dwordx4 v[162:165], v[146:147], off offset:16
	global_load_dwordx4 v[166:169], v[146:147], off offset:512
	global_load_dwordx4 v[170:173], v[146:147], off offset:528
	v_lshlrev_b64 v[148:149], 10, v[150:151]
	v_lshl_add_u64 v[148:149], v[148:149], 0, v[144:145]
	v_lshlrev_b64 v[148:149], 2, v[148:149]
	v_lshl_add_u64 v[176:177], s[8:9], 0, v[148:149]
	v_lshl_add_u64 v[180:181], s[62:63], 0, v[148:149]
	s_mov_b64 s[78:79], 0x10000
	s_mov_b64 s[80:81], 0x50000
	s_and_b64 vcc, exec, s[0:1]
	s_mov_b64 s[0:1], -1
	global_load_dwordx4 v[184:187], v[176:177], off
	global_load_dwordx4 v[188:191], v[176:177], off offset:16
	global_load_dwordx4 v[192:195], v[176:177], off offset:512
	global_load_dwordx4 v[196:199], v[176:177], off offset:528
	v_lshl_add_u64 v[176:177], v[176:177], 0, s[78:79]
	global_load_dwordx4 v[200:203], v[176:177], off
	global_load_dwordx4 v[204:207], v[176:177], off offset:16
	global_load_dwordx4 v[212:215], v[176:177], off offset:512
	global_load_dwordx4 v[216:219], v[176:177], off offset:528
	v_lshl_add_u64 v[176:177], v[176:177], 0, s[78:79]
	global_load_dwordx4 v[220:223], v[176:177], off
	global_load_dwordx4 v[224:227], v[176:177], off offset:16
	global_load_dwordx4 v[228:231], v[176:177], off offset:512
	global_load_dwordx4 v[232:235], v[176:177], off offset:528
	v_lshl_add_u64 v[176:177], v[176:177], 0, s[78:79]
	global_load_dwordx4 v[236:239], v[176:177], off
	global_load_dwordx4 v[240:243], v[176:177], off offset:16
	global_load_dwordx4 v[244:247], v[176:177], off offset:512
	global_load_dwordx4 v[248:251], v[176:177], off offset:528
	v_lshl_add_u64 v[176:177], v[176:177], 0, s[80:81]
	s_waitcnt vmcnt(16)
	v_pk_mul_f32 v[158:159], v[158:159], 0.5 op_sel_hi:[1,0]
	v_pk_mul_f32 v[160:161], v[160:161], 0.5 op_sel_hi:[1,0]
	v_pk_mul_f32 v[162:163], v[162:163], 0.5 op_sel_hi:[1,0]
	v_pk_mul_f32 v[164:165], v[164:165], 0.5 op_sel_hi:[1,0]
	v_pk_mul_f32 v[166:167], v[166:167], 0.5 op_sel_hi:[1,0]
	v_pk_mul_f32 v[168:169], v[168:169], 0.5 op_sel_hi:[1,0]
	v_pk_mul_f32 v[170:171], v[170:171], 0.5 op_sel_hi:[1,0]
	v_pk_mul_f32 v[172:173], v[172:173], 0.5 op_sel_hi:[1,0]
	s_waitcnt vmcnt(15)
	v_pk_fma_f32 v[126:127], v[126:127], v[160:161], v[186:187]
	v_pk_fma_f32 v[124:125], v[124:125], v[158:159], v[184:185]
	global_store_dwordx4 v[180:181], v[124:127], off
	global_load_dwordx4 v[184:187], v[176:177], off
	s_waitcnt vmcnt(16)
	v_pk_fma_f32 v[122:123], v[122:123], v[164:165], v[190:191]
	v_pk_fma_f32 v[120:121], v[120:121], v[162:163], v[188:189]
	global_store_dwordx4 v[180:181], v[120:123], off offset:16
	global_load_dwordx4 v[188:191], v[176:177], off offset:16
	s_waitcnt vmcnt(17)
	v_pk_fma_f32 v[118:119], v[118:119], v[168:169], v[194:195]
	v_pk_fma_f32 v[116:117], v[116:117], v[166:167], v[192:193]
	global_store_dwordx4 v[180:181], v[116:119], off offset:512
	global_load_dwordx4 v[192:195], v[176:177], off offset:512
	s_waitcnt vmcnt(18)
	v_pk_fma_f32 v[106:107], v[106:107], v[172:173], v[198:199]
	v_pk_fma_f32 v[104:105], v[104:105], v[170:171], v[196:197]
	global_store_dwordx4 v[180:181], v[104:107], off offset:528
	v_lshl_add_u64 v[180:181], v[180:181], 0, s[78:79]
	global_load_dwordx4 v[196:199], v[176:177], off offset:528
	v_lshl_add_u64 v[176:177], v[176:177], 0, s[78:79]
	s_waitcnt vmcnt(19)
	v_pk_fma_f32 v[114:115], v[114:115], v[160:161], v[202:203]
	v_pk_fma_f32 v[112:113], v[112:113], v[158:159], v[200:201]
	global_store_dwordx4 v[180:181], v[112:115], off
	global_load_dwordx4 v[200:203], v[176:177], off
	s_waitcnt vmcnt(20)
	v_pk_fma_f32 v[110:111], v[110:111], v[164:165], v[206:207]
	v_pk_fma_f32 v[108:109], v[108:109], v[162:163], v[204:205]
	global_store_dwordx4 v[180:181], v[108:111], off offset:16
	global_load_dwordx4 v[204:207], v[176:177], off offset:16
	s_waitcnt vmcnt(21)
	v_pk_fma_f32 v[102:103], v[102:103], v[168:169], v[214:215]
	v_pk_fma_f32 v[100:101], v[100:101], v[166:167], v[212:213]
	global_store_dwordx4 v[180:181], v[100:103], off offset:512
	global_load_dwordx4 v[212:215], v[176:177], off offset:512
	s_waitcnt vmcnt(22)
	v_pk_fma_f32 v[90:91], v[90:91], v[172:173], v[218:219]
	v_pk_fma_f32 v[88:89], v[88:89], v[170:171], v[216:217]
	global_store_dwordx4 v[180:181], v[88:91], off offset:528
	v_lshl_add_u64 v[180:181], v[180:181], 0, s[78:79]
	global_load_dwordx4 v[216:219], v[176:177], off offset:528
	v_lshl_add_u64 v[176:177], v[176:177], 0, s[78:79]
	s_waitcnt vmcnt(23)
	v_pk_fma_f32 v[98:99], v[98:99], v[160:161], v[222:223]
	v_pk_fma_f32 v[96:97], v[96:97], v[158:159], v[220:221]
	global_store_dwordx4 v[180:181], v[96:99], off
	global_load_dwordx4 v[220:223], v[176:177], off
	s_waitcnt vmcnt(24)
	v_pk_fma_f32 v[94:95], v[94:95], v[164:165], v[226:227]
	v_pk_fma_f32 v[92:93], v[92:93], v[162:163], v[224:225]
	global_store_dwordx4 v[180:181], v[92:95], off offset:16
	global_load_dwordx4 v[224:227], v[176:177], off offset:16
	s_waitcnt vmcnt(25)
	v_pk_fma_f32 v[86:87], v[86:87], v[168:169], v[230:231]
	v_pk_fma_f32 v[84:85], v[84:85], v[166:167], v[228:229]
	global_store_dwordx4 v[180:181], v[84:87], off offset:512
	global_load_dwordx4 v[228:231], v[176:177], off offset:512
	s_waitcnt vmcnt(26)
	v_pk_fma_f32 v[74:75], v[74:75], v[172:173], v[234:235]
	v_pk_fma_f32 v[72:73], v[72:73], v[170:171], v[232:233]
	global_store_dwordx4 v[180:181], v[72:75], off offset:528
	v_lshl_add_u64 v[180:181], v[180:181], 0, s[78:79]
	global_load_dwordx4 v[232:235], v[176:177], off offset:528
	v_lshl_add_u64 v[176:177], v[176:177], 0, s[78:79]
	s_waitcnt vmcnt(27)
	v_pk_fma_f32 v[82:83], v[82:83], v[160:161], v[238:239]
	v_pk_fma_f32 v[80:81], v[80:81], v[158:159], v[236:237]
	global_store_dwordx4 v[180:181], v[80:83], off
	global_load_dwordx4 v[236:239], v[176:177], off
	s_waitcnt vmcnt(28)
	v_pk_fma_f32 v[78:79], v[78:79], v[164:165], v[242:243]
	v_pk_fma_f32 v[76:77], v[76:77], v[162:163], v[240:241]
	global_store_dwordx4 v[180:181], v[76:79], off offset:16
	global_load_dwordx4 v[240:243], v[176:177], off offset:16
	s_waitcnt vmcnt(29)
	v_pk_fma_f32 v[70:71], v[70:71], v[168:169], v[246:247]
	v_pk_fma_f32 v[68:69], v[68:69], v[166:167], v[244:245]
	global_store_dwordx4 v[180:181], v[68:71], off offset:512
	global_load_dwordx4 v[244:247], v[176:177], off offset:512
	s_waitcnt vmcnt(30)
	v_pk_fma_f32 v[66:67], v[66:67], v[172:173], v[250:251]
	v_pk_fma_f32 v[64:65], v[64:65], v[170:171], v[248:249]
	global_store_dwordx4 v[180:181], v[64:67], off offset:528
	v_lshl_add_u64 v[180:181], v[180:181], 0, s[80:81]
	global_load_dwordx4 v[248:251], v[176:177], off offset:528
	s_waitcnt vmcnt(30)
	v_pk_fma_f32 v[62:63], v[62:63], v[160:161], v[186:187]
	v_pk_fma_f32 v[60:61], v[60:61], v[158:159], v[184:185]
	global_store_dwordx4 v[180:181], v[60:63], off
	s_waitcnt vmcnt(29)
	v_pk_fma_f32 v[58:59], v[58:59], v[164:165], v[190:191]
	v_pk_fma_f32 v[56:57], v[56:57], v[162:163], v[188:189]
	global_store_dwordx4 v[180:181], v[56:59], off offset:16
	s_waitcnt vmcnt(28)
	v_pk_fma_f32 v[54:55], v[54:55], v[168:169], v[194:195]
	v_pk_fma_f32 v[52:53], v[52:53], v[166:167], v[192:193]
	global_store_dwordx4 v[180:181], v[52:55], off offset:512
	s_waitcnt vmcnt(27)
	v_pk_fma_f32 v[42:43], v[42:43], v[172:173], v[198:199]
	v_pk_fma_f32 v[40:41], v[40:41], v[170:171], v[196:197]
	global_store_dwordx4 v[180:181], v[40:43], off offset:528
	v_lshl_add_u64 v[180:181], v[180:181], 0, s[78:79]
	s_waitcnt vmcnt(26)
	v_pk_fma_f32 v[50:51], v[50:51], v[160:161], v[202:203]
	v_pk_fma_f32 v[48:49], v[48:49], v[158:159], v[200:201]
	global_store_dwordx4 v[180:181], v[48:51], off
	s_waitcnt vmcnt(25)
	v_pk_fma_f32 v[46:47], v[46:47], v[164:165], v[206:207]
	v_pk_fma_f32 v[44:45], v[44:45], v[162:163], v[204:205]
	global_store_dwordx4 v[180:181], v[44:47], off offset:16
	s_waitcnt vmcnt(24)
	v_pk_fma_f32 v[38:39], v[38:39], v[168:169], v[214:215]
	v_pk_fma_f32 v[36:37], v[36:37], v[166:167], v[212:213]
	global_store_dwordx4 v[180:181], v[36:39], off offset:512
	s_waitcnt vmcnt(23)
	v_pk_fma_f32 v[26:27], v[26:27], v[172:173], v[218:219]
	v_pk_fma_f32 v[24:25], v[24:25], v[170:171], v[216:217]
	global_store_dwordx4 v[180:181], v[24:27], off offset:528
	v_lshl_add_u64 v[180:181], v[180:181], 0, s[78:79]
	s_waitcnt vmcnt(22)
	v_pk_fma_f32 v[34:35], v[34:35], v[160:161], v[222:223]
	v_pk_fma_f32 v[32:33], v[32:33], v[158:159], v[220:221]
	global_store_dwordx4 v[180:181], v[32:35], off
	s_waitcnt vmcnt(21)
	v_pk_fma_f32 v[30:31], v[30:31], v[164:165], v[226:227]
	v_pk_fma_f32 v[28:29], v[28:29], v[162:163], v[224:225]
	global_store_dwordx4 v[180:181], v[28:31], off offset:16
	s_waitcnt vmcnt(20)
	v_pk_fma_f32 v[22:23], v[22:23], v[168:169], v[230:231]
	v_pk_fma_f32 v[20:21], v[20:21], v[166:167], v[228:229]
	global_store_dwordx4 v[180:181], v[20:23], off offset:512
	s_waitcnt vmcnt(19)
	v_pk_fma_f32 v[10:11], v[10:11], v[172:173], v[234:235]
	v_pk_fma_f32 v[8:9], v[8:9], v[170:171], v[232:233]
	global_store_dwordx4 v[180:181], v[8:11], off offset:528
	v_lshl_add_u64 v[180:181], v[180:181], 0, s[78:79]
	s_waitcnt vmcnt(18)
	v_pk_fma_f32 v[18:19], v[18:19], v[160:161], v[238:239]
	v_pk_fma_f32 v[16:17], v[16:17], v[158:159], v[236:237]
	global_store_dwordx4 v[180:181], v[16:19], off
	s_waitcnt vmcnt(17)
	v_pk_fma_f32 v[14:15], v[14:15], v[164:165], v[242:243]
	v_pk_fma_f32 v[12:13], v[12:13], v[162:163], v[240:241]
	global_store_dwordx4 v[180:181], v[12:15], off offset:16
	s_waitcnt vmcnt(16)
	v_pk_fma_f32 v[6:7], v[6:7], v[168:169], v[246:247]
	v_pk_fma_f32 v[4:5], v[4:5], v[166:167], v[244:245]
	global_store_dwordx4 v[180:181], v[4:7], off offset:512
	s_waitcnt vmcnt(15)
	v_pk_fma_f32 v[2:3], v[2:3], v[172:173], v[250:251]
	v_pk_fma_f32 v[0:1], v[0:1], v[170:171], v[248:249]
	global_store_dwordx4 v[180:181], v[0:3], off offset:528
	s_cbranch_vccnz .LBB0_1112
	s_andn2_b64 vcc, exec, s[6:7]
	s_cbranch_vccnz .LBB0_1111
	s_barrier
	s_branch .LBB0_1111
